# v10 + SwiGLU epilogue: rs^2 folded into the reciprocal (pk_fma(e,m,m)), 5 fewer VALU per row group
# speedup vs baseline: 1.0091x; 1.0091x over previous
; __device__ __forceinline__ unsigned cvt_pk_bf16(float lo, float hi) { unsigned r; asm volatile("v_cvt_pk_bf16_f32 %0, %1, %2" : "=v"(r) : "v"(lo), "v"(hi)); return r; }
; __device__ __forceinline__ float ss_val(u64 v) { return (float)v * (1.0f / 1099511627776.0f); }
;     __device__ __forceinline__ void operator()(const f32x4 (&acc)[2][2][4][2], const Unit& u, const Unit& nxt, bool has_next, int wr, int wc, int fr, int fq) const {
;     ...
;         for (int g = 0; g < 8; ++g) {
;             const int ai = g >> 2, m = g & 3;
;             const float rs = __builtin_amdgcn_rsqf(ss_val(cur[g]) * inv_k + eps), rsn = rs * -1.44269504089f, rs2 = rs * rs;
;             float h[8];
; #pragma unroll
;             for (int n = 0; n < 2; ++n)
; #pragma unroll
;                 for (int jp = 0; jp < 2; ++jp) {
;                     const f32x2v av = {acc[ai][0][m][n][2 * jp], acc[ai][0][m][n][2 * jp + 1]}, gv = {acc[ai][1][m][n][2 * jp], acc[ai][1][m][n][2 * jp + 1]};
;                     const f32x2v t = (av * gv) * rs2, y = gv * rsn;
;                     f32x2v ex; ex.x = __builtin_amdgcn_exp2f(y.x); ex.y = __builtin_amdgcn_exp2f(y.y);
;                     const f32x2v d = ex + 1.0f;
;                     f32x2v r; r.x = __builtin_amdgcn_rcpf(d.x); r.y = __builtin_amdgcn_rcpf(d.y);
;                     const f32x2v o = t * r;
;                     h[4 * n + 2 * jp] = o.x; h[4 * n + 2 * jp + 1] = o.y;
;                 }
;             u32x4 w; w.x = cvt_pk_bf16(h[0], h[1]); w.y = cvt_pk_bf16(h[2], h[3]); w.z = cvt_pk_bf16(h[4], h[5]); w.w = cvt_pk_bf16(h[6], h[7]);
;             *(u32x4*)(O + (size_t)(row0 + ai * HALF + m * 16) * ldc + col0) = w;
.LBB0_180:
	s_waitcnt vmcnt(0)
	v_or_b32_e32 v185, 16, v168
	v_pk_mul_f32 v[124:125], v[124:125], v[116:117]
	v_cvt_f32_u32_e32 v172, v172
	v_cvt_f32_u32_e32 v173, v173
	v_fmamk_f32 v172, v173, 0x4f800000, v172
	v_fmamk_f32 v169, v172, 0x26800000, v180
	v_mov_b32_e32 v232, v169
	v_rsq_f32_e32 v186, v169
	v_pk_mul_f32 v[120:121], v[120:121], v[112:113]
	v_pk_mul_f32 v[126:127], v[126:127], v[118:119]
	v_pk_mul_f32 v[122:123], v[122:123], v[114:115]
	v_mul_f32_e32 v184, 0xbfb8aa3b, v186
	v_pk_mul_f32 v[116:117], v[116:117], v[184:185] op_sel_hi:[1,0]
	v_pk_mul_f32 v[112:113], v[112:113], v[184:185] op_sel_hi:[1,0]
	v_exp_f32_e32 v116, v116
	v_exp_f32_e32 v117, v117
	v_pk_mul_f32 v[118:119], v[118:119], v[184:185] op_sel_hi:[1,0]
	v_exp_f32_e32 v112, v112
	v_exp_f32_e32 v113, v113
	v_pk_mul_f32 v[114:115], v[114:115], v[184:185] op_sel_hi:[1,0]
	v_exp_f32_e32 v118, v118
	v_exp_f32_e32 v119, v119
	v_exp_f32_e32 v114, v114
	v_exp_f32_e32 v115, v115
	v_pk_fma_f32 v[116:117], v[116:117], v[232:233], v[232:233] op_sel_hi:[1,0,0]
	v_pk_fma_f32 v[112:113], v[112:113], v[232:233], v[232:233] op_sel_hi:[1,0,0]
	v_rcp_f32_e32 v116, v116
	v_rcp_f32_e32 v117, v117
	v_pk_fma_f32 v[118:119], v[118:119], v[232:233], v[232:233] op_sel_hi:[1,0,0]
	v_rcp_f32_e32 v112, v112
	v_rcp_f32_e32 v113, v113
	v_pk_fma_f32 v[114:115], v[114:115], v[232:233], v[232:233] op_sel_hi:[1,0,0]
	v_rcp_f32_e32 v118, v118
	v_rcp_f32_e32 v119, v119
	v_rcp_f32_e32 v114, v114
	v_rcp_f32_e32 v115, v115
	v_or_b32_e32 v187, 32, v168
	v_pk_mul_f32 v[116:117], v[124:125], v[116:117]
	v_pk_mul_f32 v[112:113], v[120:121], v[112:113]
	v_pk_mul_f32 v[118:119], v[126:127], v[118:119]
	v_pk_mul_f32 v[114:115], v[122:123], v[114:115]
	v_cvt_pk_bf16_f32 v116, v116, v117
	v_cvt_pk_bf16_f32 v117, v118, v119
	v_cvt_pk_bf16_f32 v118, v112, v113
	v_lshl_or_b32 v182, s70, 7, v176
	v_cvt_pk_bf16_f32 v119, v114, v115
	v_ashrrev_i32_e32 v183, 31, v182
	v_mov_b64_e32 v[112:113], s[24:25]
	v_cvt_f32_u32_e32 v170, v170
	v_cvt_f32_u32_e32 v171, v171
	v_fmamk_f32 v170, v171, 0x4f800000, v170
	v_fmamk_f32 v114, v170, 0x26800000, v180
	v_mov_b32_e32 v234, v114
	v_rsq_f32_e32 v122, v114
	v_mad_i64_i32 v[120:121], s[56:57], v168, s69, v[112:113]
	v_lshlrev_b64 v[114:115], 1, v[182:183]
	v_lshl_add_u64 v[120:121], v[120:121], 0, v[114:115]
	global_store_dwordx4 v[120:121], v[116:119], off
	v_pk_mul_f32 v[104:105], v[104:105], v[96:97]
	v_pk_mul_f32 v[108:109], v[108:109], v[100:101]
	v_mul_f32_e32 v116, 0xbfb8aa3b, v122
	v_pk_mul_f32 v[96:97], v[96:97], v[116:117] op_sel_hi:[1,0]
	v_pk_mul_f32 v[100:101], v[100:101], v[116:117] op_sel_hi:[1,0]
	v_pk_mul_f32 v[106:107], v[106:107], v[98:99]
	v_exp_f32_e32 v96, v96
	v_exp_f32_e32 v97, v97
	v_pk_mul_f32 v[98:99], v[98:99], v[116:117] op_sel_hi:[1,0]
	v_exp_f32_e32 v100, v100
	v_exp_f32_e32 v101, v101
	v_exp_f32_e32 v98, v98
	v_exp_f32_e32 v99, v99
	v_pk_fma_f32 v[96:97], v[96:97], v[234:235], v[234:235] op_sel_hi:[1,0,0]
	v_pk_fma_f32 v[100:101], v[100:101], v[234:235], v[234:235] op_sel_hi:[1,0,0]
	v_rcp_f32_e32 v96, v96
	v_rcp_f32_e32 v97, v97
	v_pk_fma_f32 v[98:99], v[98:99], v[234:235], v[234:235] op_sel_hi:[1,0,0]
	v_rcp_f32_e32 v100, v100
	v_rcp_f32_e32 v101, v101
	v_rcp_f32_e32 v98, v98
	v_rcp_f32_e32 v99, v99
	v_pk_mul_f32 v[104:105], v[104:105], v[96:97]
	v_pk_mul_f32 v[100:101], v[108:109], v[100:101]
	v_pk_mul_f32 v[106:107], v[106:107], v[98:99]
	v_pk_mul_f32 v[110:111], v[110:111], v[102:103]
	v_pk_mul_f32 v[102:103], v[102:103], v[116:117] op_sel_hi:[1,0]
	v_cvt_pk_bf16_f32 v96, v100, v101
	v_exp_f32_e32 v102, v102
	v_exp_f32_e32 v103, v103
	s_nop 0
	v_pk_fma_f32 v[102:103], v[102:103], v[234:235], v[234:235] op_sel_hi:[1,0,0]
	v_rcp_f32_e32 v102, v102
	v_rcp_f32_e32 v103, v103
	s_nop 0
	v_pk_mul_f32 v[102:103], v[110:111], v[102:103]
	v_cvt_f32_u32_e32 v166, v166
	v_cvt_f32_u32_e32 v167, v167
	v_fmamk_f32 v166, v167, 0x4f800000, v166
	v_fmamk_f32 v100, v166, 0x26800000, v180
	v_mov_b32_e32 v236, v100
	v_cvt_pk_bf16_f32 v97, v102, v103
	v_rsq_f32_e32 v102, v100
	v_mad_i64_i32 v[100:101], s[56:57], v185, s69, v[112:113]
	v_lshl_add_u64 v[100:101], v[100:101], 0, v[114:115]
	v_cvt_pk_bf16_f32 v98, v104, v105
	v_cvt_pk_bf16_f32 v99, v106, v107
	global_store_dwordx4 v[100:101], v[96:99], off
	v_pk_mul_f32 v[88:89], v[88:89], v[80:81]
	v_pk_mul_f32 v[92:93], v[92:93], v[84:85]
	v_mul_f32_e32 v96, 0xbfb8aa3b, v102
	v_pk_mul_f32 v[80:81], v[80:81], v[96:97] op_sel_hi:[1,0]
	v_pk_mul_f32 v[84:85], v[84:85], v[96:97] op_sel_hi:[1,0]
	v_pk_mul_f32 v[90:91], v[90:91], v[82:83]
	v_exp_f32_e32 v80, v80
	v_exp_f32_e32 v81, v81
	v_pk_mul_f32 v[82:83], v[82:83], v[96:97] op_sel_hi:[1,0]
	v_exp_f32_e32 v84, v84
	v_exp_f32_e32 v85, v85
	v_exp_f32_e32 v82, v82
	v_exp_f32_e32 v83, v83
	v_pk_fma_f32 v[80:81], v[80:81], v[236:237], v[236:237] op_sel_hi:[1,0,0]
	v_pk_fma_f32 v[84:85], v[84:85], v[236:237], v[236:237] op_sel_hi:[1,0,0]
	v_rcp_f32_e32 v80, v80
	v_rcp_f32_e32 v81, v81
	v_pk_fma_f32 v[82:83], v[82:83], v[236:237], v[236:237] op_sel_hi:[1,0,0]
	v_rcp_f32_e32 v84, v84
	v_rcp_f32_e32 v85, v85
	v_rcp_f32_e32 v82, v82
	v_rcp_f32_e32 v83, v83
	v_pk_mul_f32 v[88:89], v[88:89], v[80:81]
	v_pk_mul_f32 v[84:85], v[92:93], v[84:85]
	v_pk_mul_f32 v[90:91], v[90:91], v[82:83]
	v_pk_mul_f32 v[94:95], v[94:95], v[86:87]
	v_pk_mul_f32 v[86:87], v[86:87], v[96:97] op_sel_hi:[1,0]
	v_cvt_pk_bf16_f32 v80, v84, v85
	v_exp_f32_e32 v86, v86
	v_exp_f32_e32 v87, v87
	s_nop 0
	v_pk_fma_f32 v[86:87], v[86:87], v[236:237], v[236:237] op_sel_hi:[1,0,0]
	v_rcp_f32_e32 v86, v86
	v_rcp_f32_e32 v87, v87
	s_nop 0
	v_pk_mul_f32 v[86:87], v[94:95], v[86:87]
	v_cvt_f32_u32_e32 v164, v164
; __device__ __forceinline__ unsigned cvt_pk_bf16(float lo, float hi) { unsigned r; asm volatile("v_cvt_pk_bf16_f32 %0, %1, %2" : "=v"(r) : "v"(lo), "v"(hi)); return r; }
; __device__ __forceinline__ float ss_val(u64 v) { return (float)v * (1.0f / 1099511627776.0f); }
;     __device__ __forceinline__ void operator()(const f32x4 (&acc)[2][2][4][2], const Unit& u, const Unit& nxt, bool has_next, int wr, int wc, int fr, int fq) const {
;     ...
;         for (int g = 0; g < 8; ++g) {
;             const int ai = g >> 2, m = g & 3;
;             const float rs = __builtin_amdgcn_rsqf(ss_val(cur[g]) * inv_k + eps), rsn = rs * -1.44269504089f, rs2 = rs * rs;
;             float h[8];
; #pragma unroll
;             for (int n = 0; n < 2; ++n)
; #pragma unroll
;                 for (int jp = 0; jp < 2; ++jp) {
;                     const f32x2v av = {acc[ai][0][m][n][2 * jp], acc[ai][0][m][n][2 * jp + 1]}, gv = {acc[ai][1][m][n][2 * jp], acc[ai][1][m][n][2 * jp + 1]};
;                     const f32x2v t = (av * gv) * rs2, y = gv * rsn;
;                     f32x2v ex; ex.x = __builtin_amdgcn_exp2f(y.x); ex.y = __builtin_amdgcn_exp2f(y.y);
;                     const f32x2v d = ex + 1.0f;
;                     f32x2v r; r.x = __builtin_amdgcn_rcpf(d.x); r.y = __builtin_amdgcn_rcpf(d.y);
;                     const f32x2v o = t * r;
;                     h[4 * n + 2 * jp] = o.x; h[4 * n + 2 * jp + 1] = o.y;
;                 }
;             u32x4 w; w.x = cvt_pk_bf16(h[0], h[1]); w.y = cvt_pk_bf16(h[2], h[3]); w.z = cvt_pk_bf16(h[4], h[5]); w.w = cvt_pk_bf16(h[6], h[7]);
;             *(u32x4*)(O + (size_t)(row0 + ai * HALF + m * 16) * ldc + col0) = w;
	v_cvt_f32_u32_e32 v165, v165
	v_fmamk_f32 v164, v165, 0x4f800000, v164
	v_fmamk_f32 v84, v164, 0x26800000, v180
	v_mov_b32_e32 v238, v84
	v_cvt_pk_bf16_f32 v81, v86, v87
	v_rsq_f32_e32 v86, v84
	v_mad_i64_i32 v[84:85], s[56:57], v187, s69, v[112:113]
	v_lshl_add_u64 v[84:85], v[84:85], 0, v[114:115]
	v_cvt_pk_bf16_f32 v82, v88, v89
	v_cvt_pk_bf16_f32 v83, v90, v91
	global_store_dwordx4 v[84:85], v[80:83], off
	v_pk_mul_f32 v[72:73], v[72:73], v[64:65]
	v_pk_mul_f32 v[76:77], v[76:77], v[68:69]
	v_mul_f32_e32 v80, 0xbfb8aa3b, v86
	v_pk_mul_f32 v[64:65], v[64:65], v[80:81] op_sel_hi:[1,0]
	v_pk_mul_f32 v[68:69], v[68:69], v[80:81] op_sel_hi:[1,0]
	v_pk_mul_f32 v[74:75], v[74:75], v[66:67]
	v_exp_f32_e32 v64, v64
	v_exp_f32_e32 v65, v65
	v_pk_mul_f32 v[66:67], v[66:67], v[80:81] op_sel_hi:[1,0]
	v_exp_f32_e32 v68, v68
	v_exp_f32_e32 v69, v69
	v_exp_f32_e32 v66, v66
	v_exp_f32_e32 v67, v67
	v_pk_fma_f32 v[64:65], v[64:65], v[238:239], v[238:239] op_sel_hi:[1,0,0]
	v_pk_fma_f32 v[68:69], v[68:69], v[238:239], v[238:239] op_sel_hi:[1,0,0]
	v_rcp_f32_e32 v64, v64
	v_rcp_f32_e32 v65, v65
	v_pk_fma_f32 v[66:67], v[66:67], v[238:239], v[238:239] op_sel_hi:[1,0,0]
	v_rcp_f32_e32 v68, v68
	v_rcp_f32_e32 v69, v69
	v_rcp_f32_e32 v66, v66
	v_rcp_f32_e32 v67, v67
	v_pk_mul_f32 v[72:73], v[72:73], v[64:65]
	v_pk_mul_f32 v[68:69], v[76:77], v[68:69]
	v_pk_mul_f32 v[74:75], v[74:75], v[66:67]
	v_pk_mul_f32 v[78:79], v[78:79], v[70:71]
	v_pk_mul_f32 v[70:71], v[70:71], v[80:81] op_sel_hi:[1,0]
	v_cvt_pk_bf16_f32 v64, v68, v69
	v_exp_f32_e32 v70, v70
	v_exp_f32_e32 v71, v71
	s_nop 0
	v_pk_fma_f32 v[70:71], v[70:71], v[238:239], v[238:239] op_sel_hi:[1,0,0]
	v_rcp_f32_e32 v70, v70
	v_rcp_f32_e32 v71, v71
	s_nop 0
	v_pk_mul_f32 v[70:71], v[78:79], v[70:71]
	v_cvt_f32_u32_e32 v162, v162
	v_cvt_f32_u32_e32 v163, v163
	v_fmamk_f32 v162, v163, 0x4f800000, v162
	v_fmamk_f32 v68, v162, 0x26800000, v180
	v_mov_b32_e32 v240, v68
	v_cvt_pk_bf16_f32 v65, v70, v71
	v_rsq_f32_e32 v70, v68
	v_or_b32_e32 v188, 48, v168
	v_mad_i64_i32 v[68:69], s[56:57], v188, s69, v[112:113]
	v_lshl_add_u64 v[68:69], v[68:69], 0, v[114:115]
	v_cvt_pk_bf16_f32 v66, v72, v73
	v_cvt_pk_bf16_f32 v67, v74, v75
	global_store_dwordx4 v[68:69], v[64:67], off
	v_pk_mul_f32 v[56:57], v[56:57], v[48:49]
	v_pk_mul_f32 v[60:61], v[60:61], v[52:53]
	v_mul_f32_e32 v64, 0xbfb8aa3b, v70
	v_pk_mul_f32 v[48:49], v[48:49], v[64:65] op_sel_hi:[1,0]
	v_pk_mul_f32 v[52:53], v[52:53], v[64:65] op_sel_hi:[1,0]
	v_pk_mul_f32 v[58:59], v[58:59], v[50:51]
	v_exp_f32_e32 v48, v48
	v_exp_f32_e32 v49, v49
	v_pk_mul_f32 v[50:51], v[50:51], v[64:65] op_sel_hi:[1,0]
	v_exp_f32_e32 v52, v52
	v_exp_f32_e32 v53, v53
	v_exp_f32_e32 v50, v50
	v_exp_f32_e32 v51, v51
	v_pk_fma_f32 v[48:49], v[48:49], v[240:241], v[240:241] op_sel_hi:[1,0,0]
	v_pk_fma_f32 v[52:53], v[52:53], v[240:241], v[240:241] op_sel_hi:[1,0,0]
	v_rcp_f32_e32 v48, v48
	v_rcp_f32_e32 v49, v49
	v_pk_fma_f32 v[50:51], v[50:51], v[240:241], v[240:241] op_sel_hi:[1,0,0]
	v_rcp_f32_e32 v52, v52
	v_rcp_f32_e32 v53, v53
	v_rcp_f32_e32 v50, v50
	v_rcp_f32_e32 v51, v51
	v_pk_mul_f32 v[56:57], v[56:57], v[48:49]
	v_pk_mul_f32 v[52:53], v[60:61], v[52:53]
	v_pk_mul_f32 v[58:59], v[58:59], v[50:51]
	v_pk_mul_f32 v[62:63], v[62:63], v[54:55]
	v_pk_mul_f32 v[54:55], v[54:55], v[64:65] op_sel_hi:[1,0]
	v_cvt_pk_bf16_f32 v48, v52, v53
	v_exp_f32_e32 v54, v54
	v_exp_f32_e32 v55, v55
	s_nop 0
	v_pk_fma_f32 v[54:55], v[54:55], v[240:241], v[240:241] op_sel_hi:[1,0,0]
	v_rcp_f32_e32 v54, v54
	v_rcp_f32_e32 v55, v55
	s_nop 0
	v_pk_mul_f32 v[54:55], v[62:63], v[54:55]
	v_cvt_f32_u32_e32 v160, v160
	v_cvt_f32_u32_e32 v161, v161
	v_fmamk_f32 v160, v161, 0x4f800000, v160
	v_fmamk_f32 v52, v160, 0x26800000, v180
	v_mov_b32_e32 v242, v52
	v_cvt_pk_bf16_f32 v49, v54, v55
	v_rsq_f32_e32 v54, v52
	v_add_u32_e32 v181, 0x80, v168
	v_mad_i64_i32 v[52:53], s[56:57], v181, s69, v[112:113]
	v_lshl_add_u64 v[52:53], v[52:53], 0, v[114:115]
	v_cvt_pk_bf16_f32 v50, v56, v57
	v_cvt_pk_bf16_f32 v51, v58, v59
	global_store_dwordx4 v[52:53], v[48:51], off
	v_pk_mul_f32 v[40:41], v[40:41], v[32:33]
	v_pk_mul_f32 v[44:45], v[44:45], v[36:37]
	v_mul_f32_e32 v48, 0xbfb8aa3b, v54
	v_pk_mul_f32 v[32:33], v[32:33], v[48:49] op_sel_hi:[1,0]
	v_pk_mul_f32 v[36:37], v[36:37], v[48:49] op_sel_hi:[1,0]
	v_pk_mul_f32 v[42:43], v[42:43], v[34:35]
	v_exp_f32_e32 v32, v32
	v_exp_f32_e32 v33, v33
	v_pk_mul_f32 v[34:35], v[34:35], v[48:49] op_sel_hi:[1,0]
	v_exp_f32_e32 v36, v36
	v_exp_f32_e32 v37, v37
	v_exp_f32_e32 v34, v34
	v_exp_f32_e32 v35, v35
	v_pk_fma_f32 v[32:33], v[32:33], v[242:243], v[242:243] op_sel_hi:[1,0,0]
	v_pk_fma_f32 v[36:37], v[36:37], v[242:243], v[242:243] op_sel_hi:[1,0,0]
	v_rcp_f32_e32 v32, v32
	v_rcp_f32_e32 v33, v33
	v_pk_fma_f32 v[34:35], v[34:35], v[242:243], v[242:243] op_sel_hi:[1,0,0]
; __device__ __forceinline__ unsigned cvt_pk_bf16(float lo, float hi) { unsigned r; asm volatile("v_cvt_pk_bf16_f32 %0, %1, %2" : "=v"(r) : "v"(lo), "v"(hi)); return r; }
; __device__ __forceinline__ float ss_val(u64 v) { return (float)v * (1.0f / 1099511627776.0f); }
;     __device__ __forceinline__ void operator()(const f32x4 (&acc)[2][2][4][2], const Unit& u, const Unit& nxt, bool has_next, int wr, int wc, int fr, int fq) const {
;     ...
;         for (int g = 0; g < 8; ++g) {
;             const int ai = g >> 2, m = g & 3;
;             const float rs = __builtin_amdgcn_rsqf(ss_val(cur[g]) * inv_k + eps), rsn = rs * -1.44269504089f, rs2 = rs * rs;
;             float h[8];
; #pragma unroll
;             for (int n = 0; n < 2; ++n)
; #pragma unroll
;                 for (int jp = 0; jp < 2; ++jp) {
;                     const f32x2v av = {acc[ai][0][m][n][2 * jp], acc[ai][0][m][n][2 * jp + 1]}, gv = {acc[ai][1][m][n][2 * jp], acc[ai][1][m][n][2 * jp + 1]};
;                     const f32x2v t = (av * gv) * rs2, y = gv * rsn;
;                     f32x2v ex; ex.x = __builtin_amdgcn_exp2f(y.x); ex.y = __builtin_amdgcn_exp2f(y.y);
;                     const f32x2v d = ex + 1.0f;
;                     f32x2v r; r.x = __builtin_amdgcn_rcpf(d.x); r.y = __builtin_amdgcn_rcpf(d.y);
;                     const f32x2v o = t * r;
;                     h[4 * n + 2 * jp] = o.x; h[4 * n + 2 * jp + 1] = o.y;
;                 }
;             u32x4 w; w.x = cvt_pk_bf16(h[0], h[1]); w.y = cvt_pk_bf16(h[2], h[3]); w.z = cvt_pk_bf16(h[4], h[5]); w.w = cvt_pk_bf16(h[6], h[7]);
;             *(u32x4*)(O + (size_t)(row0 + ai * HALF + m * 16) * ldc + col0) = w;
;         }
;         if (has_next) { u64 x = 0;
; #pragma unroll
;             for (int g = 0; g < 8; ++g) x |= warm[g];
;             asm volatile("" :: "v"((unsigned)x), "v"((unsigned)(x >> 32))); }
	v_rcp_f32_e32 v36, v36
	v_rcp_f32_e32 v37, v37
	v_rcp_f32_e32 v34, v34
	v_rcp_f32_e32 v35, v35
	v_pk_mul_f32 v[40:41], v[40:41], v[32:33]
	v_pk_mul_f32 v[36:37], v[44:45], v[36:37]
	v_pk_mul_f32 v[42:43], v[42:43], v[34:35]
	v_pk_mul_f32 v[46:47], v[46:47], v[38:39]
	v_pk_mul_f32 v[38:39], v[38:39], v[48:49] op_sel_hi:[1,0]
	v_cvt_pk_bf16_f32 v32, v36, v37
	v_exp_f32_e32 v38, v38
	v_exp_f32_e32 v39, v39
	s_nop 0
	v_pk_fma_f32 v[38:39], v[38:39], v[242:243], v[242:243] op_sel_hi:[1,0,0]
	v_rcp_f32_e32 v38, v38
	v_rcp_f32_e32 v39, v39
	s_nop 0
	v_pk_mul_f32 v[38:39], v[46:47], v[38:39]
	v_cvt_f32_u32_e32 v158, v158
	v_cvt_f32_u32_e32 v159, v159
	v_fmamk_f32 v158, v159, 0x4f800000, v158
	v_fmamk_f32 v36, v158, 0x26800000, v180
	v_mov_b32_e32 v244, v36
	v_cvt_pk_bf16_f32 v33, v38, v39
	v_rsq_f32_e32 v38, v36
	v_add_u32_e32 v173, 0x90, v168
	v_mad_i64_i32 v[36:37], s[56:57], v173, s69, v[112:113]
	v_lshl_add_u64 v[36:37], v[36:37], 0, v[114:115]
	v_cvt_pk_bf16_f32 v34, v40, v41
	v_cvt_pk_bf16_f32 v35, v42, v43
	global_store_dwordx4 v[36:37], v[32:35], off
	v_pk_mul_f32 v[24:25], v[24:25], v[16:17]
	v_pk_mul_f32 v[28:29], v[28:29], v[20:21]
	v_mul_f32_e32 v32, 0xbfb8aa3b, v38
	v_pk_mul_f32 v[16:17], v[16:17], v[32:33] op_sel_hi:[1,0]
	v_pk_mul_f32 v[20:21], v[20:21], v[32:33] op_sel_hi:[1,0]
	v_pk_mul_f32 v[26:27], v[26:27], v[18:19]
	v_exp_f32_e32 v16, v16
	v_exp_f32_e32 v17, v17
	v_pk_mul_f32 v[18:19], v[18:19], v[32:33] op_sel_hi:[1,0]
	v_exp_f32_e32 v20, v20
	v_exp_f32_e32 v21, v21
	v_exp_f32_e32 v18, v18
	v_exp_f32_e32 v19, v19
	v_pk_fma_f32 v[16:17], v[16:17], v[244:245], v[244:245] op_sel_hi:[1,0,0]
	v_pk_fma_f32 v[20:21], v[20:21], v[244:245], v[244:245] op_sel_hi:[1,0,0]
	v_rcp_f32_e32 v16, v16
	v_rcp_f32_e32 v17, v17
	v_pk_fma_f32 v[18:19], v[18:19], v[244:245], v[244:245] op_sel_hi:[1,0,0]
	v_rcp_f32_e32 v20, v20
	v_rcp_f32_e32 v21, v21
	v_rcp_f32_e32 v18, v18
	v_rcp_f32_e32 v19, v19
	v_pk_mul_f32 v[24:25], v[24:25], v[16:17]
	v_pk_mul_f32 v[20:21], v[28:29], v[20:21]
	v_pk_mul_f32 v[26:27], v[26:27], v[18:19]
	v_pk_mul_f32 v[30:31], v[30:31], v[22:23]
	v_pk_mul_f32 v[22:23], v[22:23], v[32:33] op_sel_hi:[1,0]
	v_cvt_pk_bf16_f32 v16, v20, v21
	v_exp_f32_e32 v22, v22
	v_exp_f32_e32 v23, v23
	s_nop 0
	v_pk_fma_f32 v[22:23], v[22:23], v[244:245], v[244:245] op_sel_hi:[1,0,0]
	v_rcp_f32_e32 v22, v22
	v_rcp_f32_e32 v23, v23
	s_nop 0
	v_pk_mul_f32 v[22:23], v[30:31], v[22:23]
	v_cvt_f32_u32_e32 v156, v156
	v_cvt_f32_u32_e32 v157, v157
	v_fmamk_f32 v156, v157, 0x4f800000, v156
	v_fmamk_f32 v20, v156, 0x26800000, v180
	v_mov_b32_e32 v246, v20
	v_cvt_pk_bf16_f32 v17, v22, v23
	v_rsq_f32_e32 v22, v20
	v_add_u32_e32 v172, 0xa0, v168
	v_mad_i64_i32 v[20:21], s[56:57], v172, s69, v[112:113]
	v_lshl_add_u64 v[20:21], v[20:21], 0, v[114:115]
	v_cvt_pk_bf16_f32 v18, v24, v25
	v_cvt_pk_bf16_f32 v19, v26, v27
	global_store_dwordx4 v[20:21], v[16:19], off
	v_pk_mul_f32 v[12:13], v[12:13], v[4:5]
	v_pk_mul_f32 v[8:9], v[8:9], v[0:1]
	v_mul_f32_e32 v16, 0xbfb8aa3b, v22
	v_pk_mul_f32 v[4:5], v[4:5], v[16:17] op_sel_hi:[1,0]
	v_pk_mul_f32 v[0:1], v[0:1], v[16:17] op_sel_hi:[1,0]
	v_exp_f32_e32 v4, v4
	v_exp_f32_e32 v5, v5
	v_pk_mul_f32 v[10:11], v[10:11], v[2:3]
	v_exp_f32_e32 v0, v0
	v_exp_f32_e32 v1, v1
	v_pk_mul_f32 v[2:3], v[2:3], v[16:17] op_sel_hi:[1,0]
	v_pk_mul_f32 v[14:15], v[14:15], v[6:7]
	v_exp_f32_e32 v2, v2
	v_exp_f32_e32 v3, v3
	v_pk_mul_f32 v[6:7], v[6:7], v[16:17] op_sel_hi:[1,0]
	v_pk_fma_f32 v[4:5], v[4:5], v[246:247], v[246:247] op_sel_hi:[1,0,0]
	v_exp_f32_e32 v6, v6
	v_exp_f32_e32 v7, v7
	v_pk_fma_f32 v[0:1], v[0:1], v[246:247], v[246:247] op_sel_hi:[1,0,0]
	v_rcp_f32_e32 v4, v4
	v_rcp_f32_e32 v5, v5
	v_rcp_f32_e32 v0, v0
	v_rcp_f32_e32 v1, v1
	v_pk_fma_f32 v[2:3], v[2:3], v[246:247], v[246:247] op_sel_hi:[1,0,0]
	v_rcp_f32_e32 v2, v2
	v_rcp_f32_e32 v3, v3
	v_pk_fma_f32 v[6:7], v[6:7], v[246:247], v[246:247] op_sel_hi:[1,0,0]
	v_rcp_f32_e32 v6, v6
	v_rcp_f32_e32 v7, v7
	v_add_u32_e32 v169, 0xb0, v168
	v_pk_mul_f32 v[4:5], v[12:13], v[4:5]
	v_pk_mul_f32 v[8:9], v[8:9], v[0:1]
	v_pk_mul_f32 v[10:11], v[10:11], v[2:3]
	v_cvt_pk_bf16_f32 v0, v4, v5
	v_mad_i64_i32 v[4:5], s[56:57], v169, s69, v[112:113]
	v_lshl_add_u64 v[4:5], v[4:5], 0, v[114:115]
	s_and_b64 vcc, exec, s[2:3]
	s_mov_b64 s[2:3], -1
	v_pk_mul_f32 v[6:7], v[14:15], v[6:7]
	s_nop 0
	v_cvt_pk_bf16_f32 v1, v6, v7
	v_cvt_pk_bf16_f32 v2, v8, v9
	v_cvt_pk_bf16_f32 v3, v10, v11
	global_store_dwordx4 v[4:5], v[0:3], off
	s_cbranch_vccnz .LBB0_171
	s_nop 0
	v_or_b32_e32 v0, v155, v153
	v_or_b32_e32 v1, v154, v152
	v_or3_b32 v0, v0, v149, v151
	v_or3_b32 v1, v1, v148, v150
	v_or3_b32 v0, v0, v145, v147
	v_or3_b32 v1, v1, v144, v146
	s_andn2_b64 vcc, exec, s[4:5]
	v_or3_b32 v0, v0, v141, v143
	v_or3_b32 v1, v1, v140, v142
	s_cbranch_vccnz .LBB0_170
	s_barrier
	s_branch .LBB0_170

; __device__ __forceinline__ unsigned cvt_pk_bf16(float lo, float hi) { unsigned r; asm volatile("v_cvt_pk_bf16_f32 %0, %1, %2" : "=v"(r) : "v"(lo), "v"(hi)); return r; }
; __device__ __forceinline__ float ss_val(u64 v) { return (float)v * (1.0f / 1099511627776.0f); }
;     __device__ __forceinline__ void operator()(const f32x4 (&acc)[2][2][4][2], const Unit& u, const Unit& nxt, bool has_next, int wr, int wc, int fr, int fq) const {
;     ...
;         for (int g = 0; g < 8; ++g) {
;             const int ai = g >> 2, m = g & 3;
;             const float rs = __builtin_amdgcn_rsqf(ss_val(cur[g]) * inv_k + eps), rsn = rs * -1.44269504089f, rs2 = rs * rs;
;             float h[8];
; #pragma unroll
;             for (int n = 0; n < 2; ++n)
; #pragma unroll
;                 for (int jp = 0; jp < 2; ++jp) {
;                     const f32x2v av = {acc[ai][0][m][n][2 * jp], acc[ai][0][m][n][2 * jp + 1]}, gv = {acc[ai][1][m][n][2 * jp], acc[ai][1][m][n][2 * jp + 1]};
;                     const f32x2v t = (av * gv) * rs2, y = gv * rsn;
;                     f32x2v ex; ex.x = __builtin_amdgcn_exp2f(y.x); ex.y = __builtin_amdgcn_exp2f(y.y);
;                     const f32x2v d = ex + 1.0f;
;                     f32x2v r; r.x = __builtin_amdgcn_rcpf(d.x); r.y = __builtin_amdgcn_rcpf(d.y);
;                     const f32x2v o = t * r;
;                     h[4 * n + 2 * jp] = o.x; h[4 * n + 2 * jp + 1] = o.y;
;                 }
;             u32x4 w; w.x = cvt_pk_bf16(h[0], h[1]); w.y = cvt_pk_bf16(h[2], h[3]); w.z = cvt_pk_bf16(h[4], h[5]); w.w = cvt_pk_bf16(h[6], h[7]);
;             *(u32x4*)(O + (size_t)(row0 + ai * HALF + m * 16) * ldc + col0) = w;
.LBB0_665:
	s_waitcnt vmcnt(0)
	v_pk_mul_f32 v[124:125], v[124:125], v[116:117]
	v_pk_mul_f32 v[120:121], v[120:121], v[112:113]
	v_cvt_f32_u32_e32 v186, v186
	v_cvt_f32_u32_e32 v187, v187
	v_fmamk_f32 v186, v187, 0x4f800000, v186
	v_fmamk_f32 v161, v186, 0x26800000, v193
	v_mov_b32_e32 v232, v161
	v_rsq_f32_e32 v161, v161
	v_pk_mul_f32 v[126:127], v[126:127], v[118:119]
	v_pk_mul_f32 v[122:123], v[122:123], v[114:115]
	v_lshl_or_b32 v186, s86, 7, v189
	v_mul_f32_e32 v194, 0xbfb8aa3b, v161
	v_pk_mul_f32 v[116:117], v[116:117], v[194:195] op_sel_hi:[1,0]
	v_pk_mul_f32 v[112:113], v[112:113], v[194:195] op_sel_hi:[1,0]
	v_exp_f32_e32 v116, v116
	v_exp_f32_e32 v117, v117
	v_pk_mul_f32 v[118:119], v[118:119], v[194:195] op_sel_hi:[1,0]
	v_exp_f32_e32 v112, v112
	v_exp_f32_e32 v113, v113
	v_pk_mul_f32 v[114:115], v[114:115], v[194:195] op_sel_hi:[1,0]
	v_exp_f32_e32 v118, v118
	v_exp_f32_e32 v119, v119
	v_exp_f32_e32 v114, v114
	v_exp_f32_e32 v115, v115
	v_pk_fma_f32 v[116:117], v[116:117], v[232:233], v[232:233] op_sel_hi:[1,0,0]
	v_pk_fma_f32 v[112:113], v[112:113], v[232:233], v[232:233] op_sel_hi:[1,0,0]
	v_rcp_f32_e32 v116, v116
	v_rcp_f32_e32 v117, v117
	v_pk_fma_f32 v[118:119], v[118:119], v[232:233], v[232:233] op_sel_hi:[1,0,0]
	v_rcp_f32_e32 v112, v112
	v_rcp_f32_e32 v113, v113
	v_pk_fma_f32 v[114:115], v[114:115], v[232:233], v[232:233] op_sel_hi:[1,0,0]
	v_rcp_f32_e32 v118, v118
	v_rcp_f32_e32 v119, v119
	v_rcp_f32_e32 v114, v114
	v_rcp_f32_e32 v115, v115
	v_pk_mul_f32 v[116:117], v[124:125], v[116:117]
	v_pk_mul_f32 v[112:113], v[120:121], v[112:113]
	v_pk_mul_f32 v[118:119], v[126:127], v[118:119]
	v_pk_mul_f32 v[114:115], v[122:123], v[114:115]
	v_cvt_pk_bf16_f32 v116, v116, v117
	v_cvt_pk_bf16_f32 v117, v118, v119
	v_cvt_pk_bf16_f32 v118, v112, v113
	v_ashrrev_i32_e32 v187, 31, v186
	v_cvt_pk_bf16_f32 v119, v114, v115
	v_mov_b64_e32 v[112:113], s[24:25]
	v_mad_i64_i32 v[120:121], s[58:59], v182, s57, v[112:113]
	v_cvt_f32_u32_e32 v184, v184
	v_cvt_f32_u32_e32 v185, v185
	v_fmamk_f32 v184, v185, 0x4f800000, v184
	v_fmamk_f32 v114, v184, 0x26800000, v193
	v_mov_b32_e32 v234, v114
	v_rsq_f32_e32 v122, v114
	v_lshlrev_b64 v[114:115], 1, v[186:187]
	v_lshl_add_u64 v[120:121], v[120:121], 0, v[114:115]
	global_store_dwordx4 v[120:121], v[116:119], off
	v_pk_mul_f32 v[104:105], v[104:105], v[96:97]
	v_pk_mul_f32 v[108:109], v[108:109], v[100:101]
	v_mul_f32_e32 v116, 0xbfb8aa3b, v122
	v_pk_mul_f32 v[96:97], v[96:97], v[116:117] op_sel_hi:[1,0]
	v_pk_mul_f32 v[100:101], v[100:101], v[116:117] op_sel_hi:[1,0]
	v_pk_mul_f32 v[106:107], v[106:107], v[98:99]
	v_exp_f32_e32 v96, v96
	v_exp_f32_e32 v97, v97
	v_pk_mul_f32 v[98:99], v[98:99], v[116:117] op_sel_hi:[1,0]
	v_exp_f32_e32 v100, v100
	v_exp_f32_e32 v101, v101
	v_exp_f32_e32 v98, v98
	v_exp_f32_e32 v99, v99
	v_pk_fma_f32 v[96:97], v[96:97], v[234:235], v[234:235] op_sel_hi:[1,0,0]
	v_pk_fma_f32 v[100:101], v[100:101], v[234:235], v[234:235] op_sel_hi:[1,0,0]
	v_rcp_f32_e32 v96, v96
	v_rcp_f32_e32 v97, v97
	v_pk_fma_f32 v[98:99], v[98:99], v[234:235], v[234:235] op_sel_hi:[1,0,0]
	v_rcp_f32_e32 v100, v100
	v_rcp_f32_e32 v101, v101
	v_rcp_f32_e32 v98, v98
	v_rcp_f32_e32 v99, v99
	v_pk_mul_f32 v[104:105], v[104:105], v[96:97]
	v_pk_mul_f32 v[100:101], v[108:109], v[100:101]
	v_pk_mul_f32 v[106:107], v[106:107], v[98:99]
	v_pk_mul_f32 v[110:111], v[110:111], v[102:103]
	v_pk_mul_f32 v[102:103], v[102:103], v[116:117] op_sel_hi:[1,0]
	v_cvt_pk_bf16_f32 v96, v100, v101
	v_exp_f32_e32 v102, v102
	v_exp_f32_e32 v103, v103
	s_nop 0
	v_pk_fma_f32 v[102:103], v[102:103], v[234:235], v[234:235] op_sel_hi:[1,0,0]
	v_rcp_f32_e32 v102, v102
	v_rcp_f32_e32 v103, v103
	s_nop 0
	v_pk_mul_f32 v[102:103], v[110:111], v[102:103]
	v_cvt_f32_u32_e32 v180, v180
	v_cvt_f32_u32_e32 v181, v181
	v_fmamk_f32 v180, v181, 0x4f800000, v180
	v_fmamk_f32 v100, v180, 0x26800000, v193
	v_mov_b32_e32 v236, v100
	v_cvt_pk_bf16_f32 v97, v102, v103
	v_rsq_f32_e32 v102, v100
	v_mad_i64_i32 v[100:101], s[58:59], v178, s57, v[112:113]
	v_lshl_add_u64 v[100:101], v[100:101], 0, v[114:115]
	v_cvt_pk_bf16_f32 v98, v104, v105
	v_cvt_pk_bf16_f32 v99, v106, v107
	global_store_dwordx4 v[100:101], v[96:99], off
	v_pk_mul_f32 v[88:89], v[88:89], v[80:81]
	v_pk_mul_f32 v[92:93], v[92:93], v[84:85]
	v_mul_f32_e32 v96, 0xbfb8aa3b, v102
	v_pk_mul_f32 v[80:81], v[80:81], v[96:97] op_sel_hi:[1,0]
	v_pk_mul_f32 v[84:85], v[84:85], v[96:97] op_sel_hi:[1,0]
	v_pk_mul_f32 v[90:91], v[90:91], v[82:83]
	v_exp_f32_e32 v80, v80
	v_exp_f32_e32 v81, v81
	v_pk_mul_f32 v[82:83], v[82:83], v[96:97] op_sel_hi:[1,0]
	v_exp_f32_e32 v84, v84
	v_exp_f32_e32 v85, v85
	v_exp_f32_e32 v82, v82
	v_exp_f32_e32 v83, v83
	v_pk_fma_f32 v[80:81], v[80:81], v[236:237], v[236:237] op_sel_hi:[1,0,0]
	v_pk_fma_f32 v[84:85], v[84:85], v[236:237], v[236:237] op_sel_hi:[1,0,0]
	v_rcp_f32_e32 v80, v80
	v_rcp_f32_e32 v81, v81
	v_pk_fma_f32 v[82:83], v[82:83], v[236:237], v[236:237] op_sel_hi:[1,0,0]
	v_rcp_f32_e32 v84, v84
	v_rcp_f32_e32 v85, v85
	v_rcp_f32_e32 v82, v82
	v_rcp_f32_e32 v83, v83
	v_pk_mul_f32 v[88:89], v[88:89], v[80:81]
	v_pk_mul_f32 v[84:85], v[92:93], v[84:85]
	v_pk_mul_f32 v[90:91], v[90:91], v[82:83]
	v_pk_mul_f32 v[94:95], v[94:95], v[86:87]
	v_pk_mul_f32 v[86:87], v[86:87], v[96:97] op_sel_hi:[1,0]
	v_cvt_pk_bf16_f32 v80, v84, v85
	v_exp_f32_e32 v86, v86
	v_exp_f32_e32 v87, v87
	s_nop 0
	v_pk_fma_f32 v[86:87], v[86:87], v[236:237], v[236:237] op_sel_hi:[1,0,0]
	v_rcp_f32_e32 v86, v86
	v_rcp_f32_e32 v87, v87
	s_nop 0
	v_pk_mul_f32 v[86:87], v[94:95], v[86:87]
	v_cvt_f32_u32_e32 v176, v176
	v_cvt_f32_u32_e32 v177, v177
	v_fmamk_f32 v176, v177, 0x4f800000, v176
; __device__ __forceinline__ unsigned cvt_pk_bf16(float lo, float hi) { unsigned r; asm volatile("v_cvt_pk_bf16_f32 %0, %1, %2" : "=v"(r) : "v"(lo), "v"(hi)); return r; }
; __device__ __forceinline__ float ss_val(u64 v) { return (float)v * (1.0f / 1099511627776.0f); }
;     __device__ __forceinline__ void operator()(const f32x4 (&acc)[2][2][4][2], const Unit& u, const Unit& nxt, bool has_next, int wr, int wc, int fr, int fq) const {
;     ...
;         for (int g = 0; g < 8; ++g) {
;             const int ai = g >> 2, m = g & 3;
;             const float rs = __builtin_amdgcn_rsqf(ss_val(cur[g]) * inv_k + eps), rsn = rs * -1.44269504089f, rs2 = rs * rs;
;             float h[8];
; #pragma unroll
;             for (int n = 0; n < 2; ++n)
; #pragma unroll
;                 for (int jp = 0; jp < 2; ++jp) {
;                     const f32x2v av = {acc[ai][0][m][n][2 * jp], acc[ai][0][m][n][2 * jp + 1]}, gv = {acc[ai][1][m][n][2 * jp], acc[ai][1][m][n][2 * jp + 1]};
;                     const f32x2v t = (av * gv) * rs2, y = gv * rsn;
;                     f32x2v ex; ex.x = __builtin_amdgcn_exp2f(y.x); ex.y = __builtin_amdgcn_exp2f(y.y);
;                     const f32x2v d = ex + 1.0f;
;                     f32x2v r; r.x = __builtin_amdgcn_rcpf(d.x); r.y = __builtin_amdgcn_rcpf(d.y);
;                     const f32x2v o = t * r;
;                     h[4 * n + 2 * jp] = o.x; h[4 * n + 2 * jp + 1] = o.y;
;                 }
;             u32x4 w; w.x = cvt_pk_bf16(h[0], h[1]); w.y = cvt_pk_bf16(h[2], h[3]); w.z = cvt_pk_bf16(h[4], h[5]); w.w = cvt_pk_bf16(h[6], h[7]);
;             *(u32x4*)(O + (size_t)(row0 + ai * HALF + m * 16) * ldc + col0) = w;
	v_fmamk_f32 v84, v176, 0x26800000, v193
	v_mov_b32_e32 v238, v84
	v_cvt_pk_bf16_f32 v81, v86, v87
	v_rsq_f32_e32 v86, v84
	v_mad_i64_i32 v[84:85], s[58:59], v174, s57, v[112:113]
	v_lshl_add_u64 v[84:85], v[84:85], 0, v[114:115]
	v_cvt_pk_bf16_f32 v82, v88, v89
	v_cvt_pk_bf16_f32 v83, v90, v91
	global_store_dwordx4 v[84:85], v[80:83], off
	v_pk_mul_f32 v[72:73], v[72:73], v[64:65]
	v_pk_mul_f32 v[76:77], v[76:77], v[68:69]
	v_mul_f32_e32 v80, 0xbfb8aa3b, v86
	v_pk_mul_f32 v[64:65], v[64:65], v[80:81] op_sel_hi:[1,0]
	v_pk_mul_f32 v[68:69], v[68:69], v[80:81] op_sel_hi:[1,0]
	v_pk_mul_f32 v[74:75], v[74:75], v[66:67]
	v_exp_f32_e32 v64, v64
	v_exp_f32_e32 v65, v65
	v_pk_mul_f32 v[66:67], v[66:67], v[80:81] op_sel_hi:[1,0]
	v_exp_f32_e32 v68, v68
	v_exp_f32_e32 v69, v69
	v_exp_f32_e32 v66, v66
	v_exp_f32_e32 v67, v67
	v_pk_fma_f32 v[64:65], v[64:65], v[238:239], v[238:239] op_sel_hi:[1,0,0]
	v_pk_fma_f32 v[68:69], v[68:69], v[238:239], v[238:239] op_sel_hi:[1,0,0]
	v_rcp_f32_e32 v64, v64
	v_rcp_f32_e32 v65, v65
	v_pk_fma_f32 v[66:67], v[66:67], v[238:239], v[238:239] op_sel_hi:[1,0,0]
	v_rcp_f32_e32 v68, v68
	v_rcp_f32_e32 v69, v69
	v_rcp_f32_e32 v66, v66
	v_rcp_f32_e32 v67, v67
	v_pk_mul_f32 v[72:73], v[72:73], v[64:65]
	v_pk_mul_f32 v[68:69], v[76:77], v[68:69]
	v_pk_mul_f32 v[74:75], v[74:75], v[66:67]
	v_pk_mul_f32 v[78:79], v[78:79], v[70:71]
	v_pk_mul_f32 v[70:71], v[70:71], v[80:81] op_sel_hi:[1,0]
	v_cvt_pk_bf16_f32 v64, v68, v69
	v_exp_f32_e32 v70, v70
	v_exp_f32_e32 v71, v71
	s_nop 0
	v_pk_fma_f32 v[70:71], v[70:71], v[238:239], v[238:239] op_sel_hi:[1,0,0]
	v_rcp_f32_e32 v70, v70
	v_rcp_f32_e32 v71, v71
	s_nop 0
	v_pk_mul_f32 v[70:71], v[78:79], v[70:71]
	v_cvt_f32_u32_e32 v172, v172
	v_cvt_f32_u32_e32 v173, v173
	v_fmamk_f32 v172, v173, 0x4f800000, v172
	v_fmamk_f32 v68, v172, 0x26800000, v193
	v_mov_b32_e32 v240, v68
	v_cvt_pk_bf16_f32 v65, v70, v71
	v_rsq_f32_e32 v70, v68
	v_mad_i64_i32 v[68:69], s[58:59], v170, s57, v[112:113]
	v_lshl_add_u64 v[68:69], v[68:69], 0, v[114:115]
	v_cvt_pk_bf16_f32 v66, v72, v73
	v_cvt_pk_bf16_f32 v67, v74, v75
	global_store_dwordx4 v[68:69], v[64:67], off
	v_pk_mul_f32 v[56:57], v[56:57], v[48:49]
	v_pk_mul_f32 v[60:61], v[60:61], v[52:53]
	v_mul_f32_e32 v64, 0xbfb8aa3b, v70
	v_pk_mul_f32 v[48:49], v[48:49], v[64:65] op_sel_hi:[1,0]
	v_pk_mul_f32 v[52:53], v[52:53], v[64:65] op_sel_hi:[1,0]
	v_pk_mul_f32 v[58:59], v[58:59], v[50:51]
	v_exp_f32_e32 v48, v48
	v_exp_f32_e32 v49, v49
	v_pk_mul_f32 v[50:51], v[50:51], v[64:65] op_sel_hi:[1,0]
	v_exp_f32_e32 v52, v52
	v_exp_f32_e32 v53, v53
	v_exp_f32_e32 v50, v50
	v_exp_f32_e32 v51, v51
	v_pk_fma_f32 v[48:49], v[48:49], v[240:241], v[240:241] op_sel_hi:[1,0,0]
	v_pk_fma_f32 v[52:53], v[52:53], v[240:241], v[240:241] op_sel_hi:[1,0,0]
	v_rcp_f32_e32 v48, v48
	v_rcp_f32_e32 v49, v49
	v_pk_fma_f32 v[50:51], v[50:51], v[240:241], v[240:241] op_sel_hi:[1,0,0]
	v_rcp_f32_e32 v52, v52
	v_rcp_f32_e32 v53, v53
	v_rcp_f32_e32 v50, v50
	v_rcp_f32_e32 v51, v51
	v_pk_mul_f32 v[56:57], v[56:57], v[48:49]
	v_pk_mul_f32 v[52:53], v[60:61], v[52:53]
	v_pk_mul_f32 v[58:59], v[58:59], v[50:51]
	v_pk_mul_f32 v[62:63], v[62:63], v[54:55]
	v_pk_mul_f32 v[54:55], v[54:55], v[64:65] op_sel_hi:[1,0]
	v_cvt_pk_bf16_f32 v48, v52, v53
	v_exp_f32_e32 v54, v54
	v_exp_f32_e32 v55, v55
	s_nop 0
	v_pk_fma_f32 v[54:55], v[54:55], v[240:241], v[240:241] op_sel_hi:[1,0,0]
	v_rcp_f32_e32 v54, v54
	v_rcp_f32_e32 v55, v55
	s_nop 0
	v_pk_mul_f32 v[54:55], v[62:63], v[54:55]
	v_cvt_f32_u32_e32 v168, v168
	v_cvt_f32_u32_e32 v169, v169
	v_fmamk_f32 v168, v169, 0x4f800000, v168
	v_fmamk_f32 v52, v168, 0x26800000, v193
	v_mov_b32_e32 v242, v52
	v_cvt_pk_bf16_f32 v49, v54, v55
	v_rsq_f32_e32 v54, v52
	v_add_u32_e32 v141, 0x80, v182
	v_mad_i64_i32 v[52:53], s[58:59], v141, s57, v[112:113]
	v_lshl_add_u64 v[52:53], v[52:53], 0, v[114:115]
	v_cvt_pk_bf16_f32 v50, v56, v57
	v_cvt_pk_bf16_f32 v51, v58, v59
	global_store_dwordx4 v[52:53], v[48:51], off
	v_pk_mul_f32 v[40:41], v[40:41], v[32:33]
	v_pk_mul_f32 v[44:45], v[44:45], v[36:37]
	v_mul_f32_e32 v48, 0xbfb8aa3b, v54
	v_pk_mul_f32 v[32:33], v[32:33], v[48:49] op_sel_hi:[1,0]
	v_pk_mul_f32 v[36:37], v[36:37], v[48:49] op_sel_hi:[1,0]
	v_pk_mul_f32 v[42:43], v[42:43], v[34:35]
	v_exp_f32_e32 v32, v32
	v_exp_f32_e32 v33, v33
	v_pk_mul_f32 v[34:35], v[34:35], v[48:49] op_sel_hi:[1,0]
	v_exp_f32_e32 v36, v36
	v_exp_f32_e32 v37, v37
	v_exp_f32_e32 v34, v34
	v_exp_f32_e32 v35, v35
	v_pk_fma_f32 v[32:33], v[32:33], v[242:243], v[242:243] op_sel_hi:[1,0,0]
	v_pk_fma_f32 v[36:37], v[36:37], v[242:243], v[242:243] op_sel_hi:[1,0,0]
	v_rcp_f32_e32 v32, v32
	v_rcp_f32_e32 v33, v33
	v_pk_fma_f32 v[34:35], v[34:35], v[242:243], v[242:243] op_sel_hi:[1,0,0]
; __device__ __forceinline__ unsigned cvt_pk_bf16(float lo, float hi) { unsigned r; asm volatile("v_cvt_pk_bf16_f32 %0, %1, %2" : "=v"(r) : "v"(lo), "v"(hi)); return r; }
; __device__ __forceinline__ float ss_val(u64 v) { return (float)v * (1.0f / 1099511627776.0f); }
;     __device__ __forceinline__ void operator()(const f32x4 (&acc)[2][2][4][2], const Unit& u, const Unit& nxt, bool has_next, int wr, int wc, int fr, int fq) const {
;     ...
;         for (int g = 0; g < 8; ++g) {
;             const int ai = g >> 2, m = g & 3;
;             const float rs = __builtin_amdgcn_rsqf(ss_val(cur[g]) * inv_k + eps), rsn = rs * -1.44269504089f, rs2 = rs * rs;
;             float h[8];
; #pragma unroll
;             for (int n = 0; n < 2; ++n)
; #pragma unroll
;                 for (int jp = 0; jp < 2; ++jp) {
;                     const f32x2v av = {acc[ai][0][m][n][2 * jp], acc[ai][0][m][n][2 * jp + 1]}, gv = {acc[ai][1][m][n][2 * jp], acc[ai][1][m][n][2 * jp + 1]};
;                     const f32x2v t = (av * gv) * rs2, y = gv * rsn;
;                     f32x2v ex; ex.x = __builtin_amdgcn_exp2f(y.x); ex.y = __builtin_amdgcn_exp2f(y.y);
;                     const f32x2v d = ex + 1.0f;
;                     f32x2v r; r.x = __builtin_amdgcn_rcpf(d.x); r.y = __builtin_amdgcn_rcpf(d.y);
;                     const f32x2v o = t * r;
;                     h[4 * n + 2 * jp] = o.x; h[4 * n + 2 * jp + 1] = o.y;
;                 }
;             u32x4 w; w.x = cvt_pk_bf16(h[0], h[1]); w.y = cvt_pk_bf16(h[2], h[3]); w.z = cvt_pk_bf16(h[4], h[5]); w.w = cvt_pk_bf16(h[6], h[7]);
;             *(u32x4*)(O + (size_t)(row0 + ai * HALF + m * 16) * ldc + col0) = w;
;         }
;         if (has_next) { u64 x = 0;
; #pragma unroll
;             for (int g = 0; g < 8; ++g) x |= warm[g];
;             asm volatile("" :: "v"((unsigned)x), "v"((unsigned)(x >> 32))); }
	v_rcp_f32_e32 v36, v36
	v_rcp_f32_e32 v37, v37
	v_rcp_f32_e32 v34, v34
	v_rcp_f32_e32 v35, v35
	v_pk_mul_f32 v[40:41], v[40:41], v[32:33]
	v_pk_mul_f32 v[36:37], v[44:45], v[36:37]
	v_pk_mul_f32 v[42:43], v[42:43], v[34:35]
	v_pk_mul_f32 v[46:47], v[46:47], v[38:39]
	v_pk_mul_f32 v[38:39], v[38:39], v[48:49] op_sel_hi:[1,0]
	v_cvt_pk_bf16_f32 v32, v36, v37
	v_exp_f32_e32 v38, v38
	v_exp_f32_e32 v39, v39
	s_nop 0
	v_pk_fma_f32 v[38:39], v[38:39], v[242:243], v[242:243] op_sel_hi:[1,0,0]
	v_rcp_f32_e32 v38, v38
	v_rcp_f32_e32 v39, v39
	s_nop 0
	v_pk_mul_f32 v[38:39], v[46:47], v[38:39]
	v_cvt_f32_u32_e32 v166, v166
	v_cvt_f32_u32_e32 v167, v167
	v_fmamk_f32 v166, v167, 0x4f800000, v166
	v_fmamk_f32 v36, v166, 0x26800000, v193
	v_mov_b32_e32 v244, v36
	v_cvt_pk_bf16_f32 v33, v38, v39
	v_rsq_f32_e32 v38, v36
	v_mad_i64_i32 v[36:37], s[58:59], v164, s57, v[112:113]
	v_lshl_add_u64 v[36:37], v[36:37], 0, v[114:115]
	v_cvt_pk_bf16_f32 v34, v40, v41
	v_cvt_pk_bf16_f32 v35, v42, v43
	global_store_dwordx4 v[36:37], v[32:35], off
	v_pk_mul_f32 v[24:25], v[24:25], v[16:17]
	v_pk_mul_f32 v[28:29], v[28:29], v[20:21]
	v_mul_f32_e32 v32, 0xbfb8aa3b, v38
	v_pk_mul_f32 v[16:17], v[16:17], v[32:33] op_sel_hi:[1,0]
	v_pk_mul_f32 v[20:21], v[20:21], v[32:33] op_sel_hi:[1,0]
	v_pk_mul_f32 v[26:27], v[26:27], v[18:19]
	v_exp_f32_e32 v16, v16
	v_exp_f32_e32 v17, v17
	v_pk_mul_f32 v[18:19], v[18:19], v[32:33] op_sel_hi:[1,0]
	v_exp_f32_e32 v20, v20
	v_exp_f32_e32 v21, v21
	v_exp_f32_e32 v18, v18
	v_exp_f32_e32 v19, v19
	v_pk_fma_f32 v[16:17], v[16:17], v[244:245], v[244:245] op_sel_hi:[1,0,0]
	v_pk_fma_f32 v[20:21], v[20:21], v[244:245], v[244:245] op_sel_hi:[1,0,0]
	v_rcp_f32_e32 v16, v16
	v_rcp_f32_e32 v17, v17
	v_pk_fma_f32 v[18:19], v[18:19], v[244:245], v[244:245] op_sel_hi:[1,0,0]
	v_rcp_f32_e32 v20, v20
	v_rcp_f32_e32 v21, v21
	v_rcp_f32_e32 v18, v18
	v_rcp_f32_e32 v19, v19
	v_pk_mul_f32 v[24:25], v[24:25], v[16:17]
	v_pk_mul_f32 v[20:21], v[28:29], v[20:21]
	v_pk_mul_f32 v[26:27], v[26:27], v[18:19]
	v_pk_mul_f32 v[30:31], v[30:31], v[22:23]
	v_pk_mul_f32 v[22:23], v[22:23], v[32:33] op_sel_hi:[1,0]
	v_cvt_pk_bf16_f32 v16, v20, v21
	v_exp_f32_e32 v22, v22
	v_exp_f32_e32 v23, v23
	s_nop 0
	v_pk_fma_f32 v[22:23], v[22:23], v[244:245], v[244:245] op_sel_hi:[1,0,0]
	v_rcp_f32_e32 v22, v22
	v_rcp_f32_e32 v23, v23
	s_nop 0
	v_pk_mul_f32 v[22:23], v[30:31], v[22:23]
	v_cvt_f32_u32_e32 v162, v162
	v_cvt_f32_u32_e32 v163, v163
	v_fmamk_f32 v162, v163, 0x4f800000, v162
	v_fmamk_f32 v20, v162, 0x26800000, v193
	v_mov_b32_e32 v246, v20
	v_cvt_pk_bf16_f32 v17, v22, v23
	v_rsq_f32_e32 v22, v20
	v_mad_i64_i32 v[20:21], s[58:59], v160, s57, v[112:113]
	v_lshl_add_u64 v[20:21], v[20:21], 0, v[114:115]
	v_cvt_pk_bf16_f32 v18, v24, v25
	v_cvt_pk_bf16_f32 v19, v26, v27
	global_store_dwordx4 v[20:21], v[16:19], off
	v_pk_mul_f32 v[12:13], v[12:13], v[4:5]
	v_pk_mul_f32 v[8:9], v[8:9], v[0:1]
	v_mul_f32_e32 v16, 0xbfb8aa3b, v22
	v_pk_mul_f32 v[4:5], v[4:5], v[16:17] op_sel_hi:[1,0]
	v_pk_mul_f32 v[0:1], v[0:1], v[16:17] op_sel_hi:[1,0]
	v_exp_f32_e32 v4, v4
	v_exp_f32_e32 v5, v5
	v_pk_mul_f32 v[10:11], v[10:11], v[2:3]
	v_exp_f32_e32 v0, v0
	v_exp_f32_e32 v1, v1
	v_pk_mul_f32 v[2:3], v[2:3], v[16:17] op_sel_hi:[1,0]
	v_pk_mul_f32 v[14:15], v[14:15], v[6:7]
	v_exp_f32_e32 v2, v2
	v_exp_f32_e32 v3, v3
	v_pk_mul_f32 v[6:7], v[6:7], v[16:17] op_sel_hi:[1,0]
	v_pk_fma_f32 v[4:5], v[4:5], v[246:247], v[246:247] op_sel_hi:[1,0,0]
	v_exp_f32_e32 v6, v6
	v_exp_f32_e32 v7, v7
	v_pk_fma_f32 v[0:1], v[0:1], v[246:247], v[246:247] op_sel_hi:[1,0,0]
	v_rcp_f32_e32 v4, v4
	v_rcp_f32_e32 v5, v5
	v_rcp_f32_e32 v0, v0
	v_rcp_f32_e32 v1, v1
	v_pk_fma_f32 v[2:3], v[2:3], v[246:247], v[246:247] op_sel_hi:[1,0,0]
	v_rcp_f32_e32 v2, v2
	v_rcp_f32_e32 v3, v3
	v_pk_fma_f32 v[6:7], v[6:7], v[246:247], v[246:247] op_sel_hi:[1,0,0]
	v_rcp_f32_e32 v6, v6
	v_rcp_f32_e32 v7, v7
	v_pk_mul_f32 v[4:5], v[12:13], v[4:5]
	v_pk_mul_f32 v[8:9], v[8:9], v[0:1]
	v_pk_mul_f32 v[10:11], v[10:11], v[2:3]
	v_cvt_pk_bf16_f32 v0, v4, v5
	v_mad_i64_i32 v[4:5], s[58:59], v140, s57, v[112:113]
	v_lshl_add_u64 v[4:5], v[4:5], 0, v[114:115]
	s_and_b64 vcc, exec, s[4:5]
	s_mov_b64 s[4:5], -1
	v_pk_mul_f32 v[6:7], v[14:15], v[6:7]
	s_nop 0
	v_cvt_pk_bf16_f32 v1, v6, v7
	v_cvt_pk_bf16_f32 v2, v8, v9
	v_cvt_pk_bf16_f32 v3, v10, v11
	global_store_dwordx4 v[4:5], v[0:3], off
	s_cbranch_vccnz .LBB0_656
	s_nop 0
	v_or_b32_e32 v0, v159, v157
	v_or_b32_e32 v1, v158, v156
	v_or3_b32 v0, v0, v153, v155
	v_or3_b32 v1, v1, v152, v154
	v_or3_b32 v0, v0, v149, v151
	v_or3_b32 v1, v1, v148, v150
	s_andn2_b64 vcc, exec, s[6:7]
	v_or3_b32 v0, v0, v143, v147
	v_or3_b32 v1, v1, v142, v146
	s_cbranch_vccnz .LBB0_655
	s_barrier
	s_branch .LBB0_655

; __device__ __forceinline__ unsigned cvt_pk_bf16(float lo, float hi) { unsigned r; asm volatile("v_cvt_pk_bf16_f32 %0, %1, %2" : "=v"(r) : "v"(lo), "v"(hi)); return r; }
; __device__ __forceinline__ float ss_val(u64 v) { return (float)v * (1.0f / 1099511627776.0f); }
;     __device__ __forceinline__ void operator()(const f32x4 (&acc)[2][2][4][2], const Unit& u, const Unit& nxt, bool has_next, int wr, int wc, int fr, int fq) const {
;     ...
;         for (int g = 0; g < 8; ++g) {
;             const int ai = g >> 2, m = g & 3;
;             const float rs = __builtin_amdgcn_rsqf(ss_val(cur[g]) * inv_k + eps), rsn = rs * -1.44269504089f, rs2 = rs * rs;
;             float h[8];
; #pragma unroll
;             for (int n = 0; n < 2; ++n)
; #pragma unroll
;                 for (int jp = 0; jp < 2; ++jp) {
;                     const f32x2v av = {acc[ai][0][m][n][2 * jp], acc[ai][0][m][n][2 * jp + 1]}, gv = {acc[ai][1][m][n][2 * jp], acc[ai][1][m][n][2 * jp + 1]};
;                     const f32x2v t = (av * gv) * rs2, y = gv * rsn;
;                     f32x2v ex; ex.x = __builtin_amdgcn_exp2f(y.x); ex.y = __builtin_amdgcn_exp2f(y.y);
;                     const f32x2v d = ex + 1.0f;
;                     f32x2v r; r.x = __builtin_amdgcn_rcpf(d.x); r.y = __builtin_amdgcn_rcpf(d.y);
;                     const f32x2v o = t * r;
;                     h[4 * n + 2 * jp] = o.x; h[4 * n + 2 * jp + 1] = o.y;
;                 }
;             u32x4 w; w.x = cvt_pk_bf16(h[0], h[1]); w.y = cvt_pk_bf16(h[2], h[3]); w.z = cvt_pk_bf16(h[4], h[5]); w.w = cvt_pk_bf16(h[6], h[7]);
;             *(u32x4*)(O + (size_t)(row0 + ai * HALF + m * 16) * ldc + col0) = w;
.LBB0_1298:
	s_waitcnt vmcnt(0)
	v_pk_mul_f32 v[124:125], v[124:125], v[116:117]
	v_pk_mul_f32 v[120:121], v[120:121], v[112:113]
	v_cvt_f32_u32_e32 v184, v184
	v_cvt_f32_u32_e32 v185, v185
	v_fmamk_f32 v184, v185, 0x4f800000, v184
	v_fmamk_f32 v159, v184, 0x26800000, v192
	v_mov_b32_e32 v232, v159
	v_rsq_f32_e32 v159, v159
	v_pk_mul_f32 v[126:127], v[126:127], v[118:119]
	v_pk_mul_f32 v[122:123], v[122:123], v[114:115]
	v_lshl_or_b32 v184, s62, 7, v188
	v_mul_f32_e32 v194, 0xbfb8aa3b, v159
	v_pk_mul_f32 v[116:117], v[116:117], v[194:195] op_sel_hi:[1,0]
	v_pk_mul_f32 v[112:113], v[112:113], v[194:195] op_sel_hi:[1,0]
	v_exp_f32_e32 v116, v116
	v_exp_f32_e32 v117, v117
	v_pk_mul_f32 v[118:119], v[118:119], v[194:195] op_sel_hi:[1,0]
	v_exp_f32_e32 v112, v112
	v_exp_f32_e32 v113, v113
	v_pk_mul_f32 v[114:115], v[114:115], v[194:195] op_sel_hi:[1,0]
	v_exp_f32_e32 v118, v118
	v_exp_f32_e32 v119, v119
	v_exp_f32_e32 v114, v114
	v_exp_f32_e32 v115, v115
	v_pk_fma_f32 v[116:117], v[116:117], v[232:233], v[232:233] op_sel_hi:[1,0,0]
	v_pk_fma_f32 v[112:113], v[112:113], v[232:233], v[232:233] op_sel_hi:[1,0,0]
	v_rcp_f32_e32 v116, v116
	v_rcp_f32_e32 v117, v117
	v_pk_fma_f32 v[118:119], v[118:119], v[232:233], v[232:233] op_sel_hi:[1,0,0]
	v_rcp_f32_e32 v112, v112
	v_rcp_f32_e32 v113, v113
	v_pk_fma_f32 v[114:115], v[114:115], v[232:233], v[232:233] op_sel_hi:[1,0,0]
	v_rcp_f32_e32 v118, v118
	v_rcp_f32_e32 v119, v119
	v_rcp_f32_e32 v114, v114
	v_rcp_f32_e32 v115, v115
	v_pk_mul_f32 v[116:117], v[124:125], v[116:117]
	v_pk_mul_f32 v[112:113], v[120:121], v[112:113]
	v_pk_mul_f32 v[118:119], v[126:127], v[118:119]
	v_pk_mul_f32 v[114:115], v[122:123], v[114:115]
	v_cvt_pk_bf16_f32 v116, v116, v117
	v_cvt_pk_bf16_f32 v117, v118, v119
	v_cvt_pk_bf16_f32 v118, v112, v113
	v_ashrrev_i32_e32 v185, 31, v184
	v_cvt_pk_bf16_f32 v119, v114, v115
	v_mov_b64_e32 v[112:113], s[24:25]
	v_mad_i64_i32 v[120:121], s[46:47], v180, s61, v[112:113]
	v_cvt_f32_u32_e32 v182, v182
	v_cvt_f32_u32_e32 v183, v183
	v_fmamk_f32 v182, v183, 0x4f800000, v182
	v_fmamk_f32 v114, v182, 0x26800000, v192
	v_mov_b32_e32 v234, v114
	v_rsq_f32_e32 v122, v114
	v_lshlrev_b64 v[114:115], 1, v[184:185]
	v_lshl_add_u64 v[120:121], v[120:121], 0, v[114:115]
	global_store_dwordx4 v[120:121], v[116:119], off
	v_pk_mul_f32 v[104:105], v[104:105], v[96:97]
	v_pk_mul_f32 v[108:109], v[108:109], v[100:101]
	v_mul_f32_e32 v116, 0xbfb8aa3b, v122
	v_pk_mul_f32 v[96:97], v[96:97], v[116:117] op_sel_hi:[1,0]
	v_pk_mul_f32 v[100:101], v[100:101], v[116:117] op_sel_hi:[1,0]
	v_pk_mul_f32 v[106:107], v[106:107], v[98:99]
	v_exp_f32_e32 v96, v96
	v_exp_f32_e32 v97, v97
	v_pk_mul_f32 v[98:99], v[98:99], v[116:117] op_sel_hi:[1,0]
	v_exp_f32_e32 v100, v100
	v_exp_f32_e32 v101, v101
	v_exp_f32_e32 v98, v98
	v_exp_f32_e32 v99, v99
	v_pk_fma_f32 v[96:97], v[96:97], v[234:235], v[234:235] op_sel_hi:[1,0,0]
	v_pk_fma_f32 v[100:101], v[100:101], v[234:235], v[234:235] op_sel_hi:[1,0,0]
	v_rcp_f32_e32 v96, v96
	v_rcp_f32_e32 v97, v97
	v_pk_fma_f32 v[98:99], v[98:99], v[234:235], v[234:235] op_sel_hi:[1,0,0]
	v_rcp_f32_e32 v100, v100
	v_rcp_f32_e32 v101, v101
	v_rcp_f32_e32 v98, v98
	v_rcp_f32_e32 v99, v99
	v_pk_mul_f32 v[104:105], v[104:105], v[96:97]
	v_pk_mul_f32 v[100:101], v[108:109], v[100:101]
	v_pk_mul_f32 v[106:107], v[106:107], v[98:99]
	v_pk_mul_f32 v[110:111], v[110:111], v[102:103]
	v_pk_mul_f32 v[102:103], v[102:103], v[116:117] op_sel_hi:[1,0]
	v_cvt_pk_bf16_f32 v96, v100, v101
	v_exp_f32_e32 v102, v102
	v_exp_f32_e32 v103, v103
	s_nop 0
	v_pk_fma_f32 v[102:103], v[102:103], v[234:235], v[234:235] op_sel_hi:[1,0,0]
	v_rcp_f32_e32 v102, v102
	v_rcp_f32_e32 v103, v103
	s_nop 0
	v_pk_mul_f32 v[102:103], v[110:111], v[102:103]
	v_cvt_f32_u32_e32 v178, v178
	v_cvt_f32_u32_e32 v179, v179
	v_fmamk_f32 v178, v179, 0x4f800000, v178
	v_fmamk_f32 v100, v178, 0x26800000, v192
	v_mov_b32_e32 v236, v100
	v_cvt_pk_bf16_f32 v97, v102, v103
	v_rsq_f32_e32 v102, v100
	v_mad_i64_i32 v[100:101], s[46:47], v176, s61, v[112:113]
	v_lshl_add_u64 v[100:101], v[100:101], 0, v[114:115]
	v_cvt_pk_bf16_f32 v98, v104, v105
	v_cvt_pk_bf16_f32 v99, v106, v107
	global_store_dwordx4 v[100:101], v[96:99], off
	v_pk_mul_f32 v[88:89], v[88:89], v[80:81]
	v_pk_mul_f32 v[92:93], v[92:93], v[84:85]
	v_mul_f32_e32 v96, 0xbfb8aa3b, v102
	v_pk_mul_f32 v[80:81], v[80:81], v[96:97] op_sel_hi:[1,0]
	v_pk_mul_f32 v[84:85], v[84:85], v[96:97] op_sel_hi:[1,0]
	v_pk_mul_f32 v[90:91], v[90:91], v[82:83]
	v_exp_f32_e32 v80, v80
	v_exp_f32_e32 v81, v81
	v_pk_mul_f32 v[82:83], v[82:83], v[96:97] op_sel_hi:[1,0]
	v_exp_f32_e32 v84, v84
	v_exp_f32_e32 v85, v85
	v_exp_f32_e32 v82, v82
	v_exp_f32_e32 v83, v83
	v_pk_fma_f32 v[80:81], v[80:81], v[236:237], v[236:237] op_sel_hi:[1,0,0]
	v_pk_fma_f32 v[84:85], v[84:85], v[236:237], v[236:237] op_sel_hi:[1,0,0]
	v_rcp_f32_e32 v80, v80
	v_rcp_f32_e32 v81, v81
	v_pk_fma_f32 v[82:83], v[82:83], v[236:237], v[236:237] op_sel_hi:[1,0,0]
	v_rcp_f32_e32 v84, v84
	v_rcp_f32_e32 v85, v85
	v_rcp_f32_e32 v82, v82
	v_rcp_f32_e32 v83, v83
	v_pk_mul_f32 v[88:89], v[88:89], v[80:81]
	v_pk_mul_f32 v[84:85], v[92:93], v[84:85]
	v_pk_mul_f32 v[90:91], v[90:91], v[82:83]
	v_pk_mul_f32 v[94:95], v[94:95], v[86:87]
	v_pk_mul_f32 v[86:87], v[86:87], v[96:97] op_sel_hi:[1,0]
	v_cvt_pk_bf16_f32 v80, v84, v85
	v_exp_f32_e32 v86, v86
	v_exp_f32_e32 v87, v87
	s_nop 0
	v_pk_fma_f32 v[86:87], v[86:87], v[236:237], v[236:237] op_sel_hi:[1,0,0]
	v_rcp_f32_e32 v86, v86
	v_rcp_f32_e32 v87, v87
	s_nop 0
	v_pk_mul_f32 v[86:87], v[94:95], v[86:87]
	v_cvt_f32_u32_e32 v174, v174
	v_cvt_f32_u32_e32 v175, v175
	v_fmamk_f32 v174, v175, 0x4f800000, v174
; __device__ __forceinline__ unsigned cvt_pk_bf16(float lo, float hi) { unsigned r; asm volatile("v_cvt_pk_bf16_f32 %0, %1, %2" : "=v"(r) : "v"(lo), "v"(hi)); return r; }
; __device__ __forceinline__ float ss_val(u64 v) { return (float)v * (1.0f / 1099511627776.0f); }
;     __device__ __forceinline__ void operator()(const f32x4 (&acc)[2][2][4][2], const Unit& u, const Unit& nxt, bool has_next, int wr, int wc, int fr, int fq) const {
;     ...
;         for (int g = 0; g < 8; ++g) {
;             const int ai = g >> 2, m = g & 3;
;             const float rs = __builtin_amdgcn_rsqf(ss_val(cur[g]) * inv_k + eps), rsn = rs * -1.44269504089f, rs2 = rs * rs;
;             float h[8];
; #pragma unroll
;             for (int n = 0; n < 2; ++n)
; #pragma unroll
;                 for (int jp = 0; jp < 2; ++jp) {
;                     const f32x2v av = {acc[ai][0][m][n][2 * jp], acc[ai][0][m][n][2 * jp + 1]}, gv = {acc[ai][1][m][n][2 * jp], acc[ai][1][m][n][2 * jp + 1]};
;                     const f32x2v t = (av * gv) * rs2, y = gv * rsn;
;                     f32x2v ex; ex.x = __builtin_amdgcn_exp2f(y.x); ex.y = __builtin_amdgcn_exp2f(y.y);
;                     const f32x2v d = ex + 1.0f;
;                     f32x2v r; r.x = __builtin_amdgcn_rcpf(d.x); r.y = __builtin_amdgcn_rcpf(d.y);
;                     const f32x2v o = t * r;
;                     h[4 * n + 2 * jp] = o.x; h[4 * n + 2 * jp + 1] = o.y;
;                 }
;             u32x4 w; w.x = cvt_pk_bf16(h[0], h[1]); w.y = cvt_pk_bf16(h[2], h[3]); w.z = cvt_pk_bf16(h[4], h[5]); w.w = cvt_pk_bf16(h[6], h[7]);
;             *(u32x4*)(O + (size_t)(row0 + ai * HALF + m * 16) * ldc + col0) = w;
	v_fmamk_f32 v84, v174, 0x26800000, v192
	v_mov_b32_e32 v238, v84
	v_cvt_pk_bf16_f32 v81, v86, v87
	v_rsq_f32_e32 v86, v84
	v_mad_i64_i32 v[84:85], s[46:47], v172, s61, v[112:113]
	v_lshl_add_u64 v[84:85], v[84:85], 0, v[114:115]
	v_cvt_pk_bf16_f32 v82, v88, v89
	v_cvt_pk_bf16_f32 v83, v90, v91
	global_store_dwordx4 v[84:85], v[80:83], off
	v_pk_mul_f32 v[72:73], v[72:73], v[64:65]
	v_pk_mul_f32 v[76:77], v[76:77], v[68:69]
	v_mul_f32_e32 v80, 0xbfb8aa3b, v86
	v_pk_mul_f32 v[64:65], v[64:65], v[80:81] op_sel_hi:[1,0]
	v_pk_mul_f32 v[68:69], v[68:69], v[80:81] op_sel_hi:[1,0]
	v_pk_mul_f32 v[74:75], v[74:75], v[66:67]
	v_exp_f32_e32 v64, v64
	v_exp_f32_e32 v65, v65
	v_pk_mul_f32 v[66:67], v[66:67], v[80:81] op_sel_hi:[1,0]
	v_exp_f32_e32 v68, v68
	v_exp_f32_e32 v69, v69
	v_exp_f32_e32 v66, v66
	v_exp_f32_e32 v67, v67
	v_pk_fma_f32 v[64:65], v[64:65], v[238:239], v[238:239] op_sel_hi:[1,0,0]
	v_pk_fma_f32 v[68:69], v[68:69], v[238:239], v[238:239] op_sel_hi:[1,0,0]
	v_rcp_f32_e32 v64, v64
	v_rcp_f32_e32 v65, v65
	v_pk_fma_f32 v[66:67], v[66:67], v[238:239], v[238:239] op_sel_hi:[1,0,0]
	v_rcp_f32_e32 v68, v68
	v_rcp_f32_e32 v69, v69
	v_rcp_f32_e32 v66, v66
	v_rcp_f32_e32 v67, v67
	v_pk_mul_f32 v[72:73], v[72:73], v[64:65]
	v_pk_mul_f32 v[68:69], v[76:77], v[68:69]
	v_pk_mul_f32 v[74:75], v[74:75], v[66:67]
	v_pk_mul_f32 v[78:79], v[78:79], v[70:71]
	v_pk_mul_f32 v[70:71], v[70:71], v[80:81] op_sel_hi:[1,0]
	v_cvt_pk_bf16_f32 v64, v68, v69
	v_exp_f32_e32 v70, v70
	v_exp_f32_e32 v71, v71
	s_nop 0
	v_pk_fma_f32 v[70:71], v[70:71], v[238:239], v[238:239] op_sel_hi:[1,0,0]
	v_rcp_f32_e32 v70, v70
	v_rcp_f32_e32 v71, v71
	s_nop 0
	v_pk_mul_f32 v[70:71], v[78:79], v[70:71]
	v_cvt_f32_u32_e32 v170, v170
	v_cvt_f32_u32_e32 v171, v171
	v_fmamk_f32 v170, v171, 0x4f800000, v170
	v_fmamk_f32 v68, v170, 0x26800000, v192
	v_mov_b32_e32 v240, v68
	v_cvt_pk_bf16_f32 v65, v70, v71
	v_rsq_f32_e32 v70, v68
	v_mad_i64_i32 v[68:69], s[46:47], v168, s61, v[112:113]
	v_lshl_add_u64 v[68:69], v[68:69], 0, v[114:115]
	v_cvt_pk_bf16_f32 v66, v72, v73
	v_cvt_pk_bf16_f32 v67, v74, v75
	global_store_dwordx4 v[68:69], v[64:67], off
	v_pk_mul_f32 v[56:57], v[56:57], v[48:49]
	v_pk_mul_f32 v[60:61], v[60:61], v[52:53]
	v_mul_f32_e32 v64, 0xbfb8aa3b, v70
	v_pk_mul_f32 v[48:49], v[48:49], v[64:65] op_sel_hi:[1,0]
	v_pk_mul_f32 v[52:53], v[52:53], v[64:65] op_sel_hi:[1,0]
	v_pk_mul_f32 v[58:59], v[58:59], v[50:51]
	v_exp_f32_e32 v48, v48
	v_exp_f32_e32 v49, v49
	v_pk_mul_f32 v[50:51], v[50:51], v[64:65] op_sel_hi:[1,0]
	v_exp_f32_e32 v52, v52
	v_exp_f32_e32 v53, v53
	v_exp_f32_e32 v50, v50
	v_exp_f32_e32 v51, v51
	v_pk_fma_f32 v[48:49], v[48:49], v[240:241], v[240:241] op_sel_hi:[1,0,0]
	v_pk_fma_f32 v[52:53], v[52:53], v[240:241], v[240:241] op_sel_hi:[1,0,0]
	v_rcp_f32_e32 v48, v48
	v_rcp_f32_e32 v49, v49
	v_pk_fma_f32 v[50:51], v[50:51], v[240:241], v[240:241] op_sel_hi:[1,0,0]
	v_rcp_f32_e32 v52, v52
	v_rcp_f32_e32 v53, v53
	v_rcp_f32_e32 v50, v50
	v_rcp_f32_e32 v51, v51
	v_pk_mul_f32 v[56:57], v[56:57], v[48:49]
	v_pk_mul_f32 v[52:53], v[60:61], v[52:53]
	v_pk_mul_f32 v[58:59], v[58:59], v[50:51]
	v_pk_mul_f32 v[62:63], v[62:63], v[54:55]
	v_pk_mul_f32 v[54:55], v[54:55], v[64:65] op_sel_hi:[1,0]
	v_cvt_pk_bf16_f32 v48, v52, v53
	v_exp_f32_e32 v54, v54
	v_exp_f32_e32 v55, v55
	s_nop 0
	v_pk_fma_f32 v[54:55], v[54:55], v[240:241], v[240:241] op_sel_hi:[1,0,0]
	v_rcp_f32_e32 v54, v54
	v_rcp_f32_e32 v55, v55
	s_nop 0
	v_pk_mul_f32 v[54:55], v[62:63], v[54:55]
	v_cvt_f32_u32_e32 v166, v166
	v_cvt_f32_u32_e32 v167, v167
	v_fmamk_f32 v166, v167, 0x4f800000, v166
	v_fmamk_f32 v52, v166, 0x26800000, v192
	v_mov_b32_e32 v242, v52
	v_cvt_pk_bf16_f32 v49, v54, v55
	v_rsq_f32_e32 v54, v52
	v_add_u32_e32 v141, 0x80, v180
	v_mad_i64_i32 v[52:53], s[46:47], v141, s61, v[112:113]
	v_lshl_add_u64 v[52:53], v[52:53], 0, v[114:115]
	v_cvt_pk_bf16_f32 v50, v56, v57
	v_cvt_pk_bf16_f32 v51, v58, v59
	global_store_dwordx4 v[52:53], v[48:51], off
	v_pk_mul_f32 v[40:41], v[40:41], v[32:33]
	v_pk_mul_f32 v[44:45], v[44:45], v[36:37]
	v_mul_f32_e32 v48, 0xbfb8aa3b, v54
	v_pk_mul_f32 v[32:33], v[32:33], v[48:49] op_sel_hi:[1,0]
	v_pk_mul_f32 v[36:37], v[36:37], v[48:49] op_sel_hi:[1,0]
	v_pk_mul_f32 v[42:43], v[42:43], v[34:35]
	v_exp_f32_e32 v32, v32
	v_exp_f32_e32 v33, v33
	v_pk_mul_f32 v[34:35], v[34:35], v[48:49] op_sel_hi:[1,0]
	v_exp_f32_e32 v36, v36
	v_exp_f32_e32 v37, v37
	v_exp_f32_e32 v34, v34
	v_exp_f32_e32 v35, v35
	v_pk_fma_f32 v[32:33], v[32:33], v[242:243], v[242:243] op_sel_hi:[1,0,0]
	v_pk_fma_f32 v[36:37], v[36:37], v[242:243], v[242:243] op_sel_hi:[1,0,0]
	v_rcp_f32_e32 v32, v32
	v_rcp_f32_e32 v33, v33
	v_pk_fma_f32 v[34:35], v[34:35], v[242:243], v[242:243] op_sel_hi:[1,0,0]
; __device__ __forceinline__ unsigned cvt_pk_bf16(float lo, float hi) { unsigned r; asm volatile("v_cvt_pk_bf16_f32 %0, %1, %2" : "=v"(r) : "v"(lo), "v"(hi)); return r; }
; __device__ __forceinline__ float ss_val(u64 v) { return (float)v * (1.0f / 1099511627776.0f); }
;     __device__ __forceinline__ void operator()(const f32x4 (&acc)[2][2][4][2], const Unit& u, const Unit& nxt, bool has_next, int wr, int wc, int fr, int fq) const {
;     ...
;         for (int g = 0; g < 8; ++g) {
;             const int ai = g >> 2, m = g & 3;
;             const float rs = __builtin_amdgcn_rsqf(ss_val(cur[g]) * inv_k + eps), rsn = rs * -1.44269504089f, rs2 = rs * rs;
;             float h[8];
; #pragma unroll
;             for (int n = 0; n < 2; ++n)
; #pragma unroll
;                 for (int jp = 0; jp < 2; ++jp) {
;                     const f32x2v av = {acc[ai][0][m][n][2 * jp], acc[ai][0][m][n][2 * jp + 1]}, gv = {acc[ai][1][m][n][2 * jp], acc[ai][1][m][n][2 * jp + 1]};
;                     const f32x2v t = (av * gv) * rs2, y = gv * rsn;
;                     f32x2v ex; ex.x = __builtin_amdgcn_exp2f(y.x); ex.y = __builtin_amdgcn_exp2f(y.y);
;                     const f32x2v d = ex + 1.0f;
;                     f32x2v r; r.x = __builtin_amdgcn_rcpf(d.x); r.y = __builtin_amdgcn_rcpf(d.y);
;                     const f32x2v o = t * r;
;                     h[4 * n + 2 * jp] = o.x; h[4 * n + 2 * jp + 1] = o.y;
;                 }
;             u32x4 w; w.x = cvt_pk_bf16(h[0], h[1]); w.y = cvt_pk_bf16(h[2], h[3]); w.z = cvt_pk_bf16(h[4], h[5]); w.w = cvt_pk_bf16(h[6], h[7]);
;             *(u32x4*)(O + (size_t)(row0 + ai * HALF + m * 16) * ldc + col0) = w;
;         }
;         if (has_next) { u64 x = 0;
; #pragma unroll
;             for (int g = 0; g < 8; ++g) x |= warm[g];
;             asm volatile("" :: "v"((unsigned)x), "v"((unsigned)(x >> 32))); }
	v_rcp_f32_e32 v36, v36
	v_rcp_f32_e32 v37, v37
	v_rcp_f32_e32 v34, v34
	v_rcp_f32_e32 v35, v35
	v_pk_mul_f32 v[40:41], v[40:41], v[32:33]
	v_pk_mul_f32 v[36:37], v[44:45], v[36:37]
	v_pk_mul_f32 v[42:43], v[42:43], v[34:35]
	v_pk_mul_f32 v[46:47], v[46:47], v[38:39]
	v_pk_mul_f32 v[38:39], v[38:39], v[48:49] op_sel_hi:[1,0]
	v_cvt_pk_bf16_f32 v32, v36, v37
	v_exp_f32_e32 v38, v38
	v_exp_f32_e32 v39, v39
	s_nop 0
	v_pk_fma_f32 v[38:39], v[38:39], v[242:243], v[242:243] op_sel_hi:[1,0,0]
	v_rcp_f32_e32 v38, v38
	v_rcp_f32_e32 v39, v39
	s_nop 0
	v_pk_mul_f32 v[38:39], v[46:47], v[38:39]
	v_cvt_f32_u32_e32 v164, v164
	v_cvt_f32_u32_e32 v165, v165
	v_fmamk_f32 v164, v165, 0x4f800000, v164
	v_fmamk_f32 v36, v164, 0x26800000, v192
	v_mov_b32_e32 v244, v36
	v_cvt_pk_bf16_f32 v33, v38, v39
	v_rsq_f32_e32 v38, v36
	v_mad_i64_i32 v[36:37], s[46:47], v162, s61, v[112:113]
	v_lshl_add_u64 v[36:37], v[36:37], 0, v[114:115]
	v_cvt_pk_bf16_f32 v34, v40, v41
	v_cvt_pk_bf16_f32 v35, v42, v43
	global_store_dwordx4 v[36:37], v[32:35], off
	v_pk_mul_f32 v[24:25], v[24:25], v[16:17]
	v_pk_mul_f32 v[28:29], v[28:29], v[20:21]
	v_mul_f32_e32 v32, 0xbfb8aa3b, v38
	v_pk_mul_f32 v[16:17], v[16:17], v[32:33] op_sel_hi:[1,0]
	v_pk_mul_f32 v[20:21], v[20:21], v[32:33] op_sel_hi:[1,0]
	v_pk_mul_f32 v[26:27], v[26:27], v[18:19]
	v_exp_f32_e32 v16, v16
	v_exp_f32_e32 v17, v17
	v_pk_mul_f32 v[18:19], v[18:19], v[32:33] op_sel_hi:[1,0]
	v_exp_f32_e32 v20, v20
	v_exp_f32_e32 v21, v21
	v_exp_f32_e32 v18, v18
	v_exp_f32_e32 v19, v19
	v_pk_fma_f32 v[16:17], v[16:17], v[244:245], v[244:245] op_sel_hi:[1,0,0]
	v_pk_fma_f32 v[20:21], v[20:21], v[244:245], v[244:245] op_sel_hi:[1,0,0]
	v_rcp_f32_e32 v16, v16
	v_rcp_f32_e32 v17, v17
	v_pk_fma_f32 v[18:19], v[18:19], v[244:245], v[244:245] op_sel_hi:[1,0,0]
	v_rcp_f32_e32 v20, v20
	v_rcp_f32_e32 v21, v21
	v_rcp_f32_e32 v18, v18
	v_rcp_f32_e32 v19, v19
	v_pk_mul_f32 v[24:25], v[24:25], v[16:17]
	v_pk_mul_f32 v[20:21], v[28:29], v[20:21]
	v_pk_mul_f32 v[26:27], v[26:27], v[18:19]
	v_pk_mul_f32 v[30:31], v[30:31], v[22:23]
	v_pk_mul_f32 v[22:23], v[22:23], v[32:33] op_sel_hi:[1,0]
	v_cvt_pk_bf16_f32 v16, v20, v21
	v_exp_f32_e32 v22, v22
	v_exp_f32_e32 v23, v23
	s_nop 0
	v_pk_fma_f32 v[22:23], v[22:23], v[244:245], v[244:245] op_sel_hi:[1,0,0]
	v_rcp_f32_e32 v22, v22
	v_rcp_f32_e32 v23, v23
	s_nop 0
	v_pk_mul_f32 v[22:23], v[30:31], v[22:23]
	v_cvt_f32_u32_e32 v160, v160
	v_cvt_f32_u32_e32 v161, v161
	v_fmamk_f32 v160, v161, 0x4f800000, v160
	v_fmamk_f32 v20, v160, 0x26800000, v192
	v_mov_b32_e32 v246, v20
	v_cvt_pk_bf16_f32 v17, v22, v23
	v_rsq_f32_e32 v22, v20
	v_mad_i64_i32 v[20:21], s[46:47], v158, s61, v[112:113]
	v_lshl_add_u64 v[20:21], v[20:21], 0, v[114:115]
	v_cvt_pk_bf16_f32 v18, v24, v25
	v_cvt_pk_bf16_f32 v19, v26, v27
	global_store_dwordx4 v[20:21], v[16:19], off
	v_pk_mul_f32 v[12:13], v[12:13], v[4:5]
	v_pk_mul_f32 v[8:9], v[8:9], v[0:1]
	v_mul_f32_e32 v16, 0xbfb8aa3b, v22
	v_pk_mul_f32 v[4:5], v[4:5], v[16:17] op_sel_hi:[1,0]
	v_pk_mul_f32 v[0:1], v[0:1], v[16:17] op_sel_hi:[1,0]
	v_exp_f32_e32 v4, v4
	v_exp_f32_e32 v5, v5
	v_pk_mul_f32 v[10:11], v[10:11], v[2:3]
	v_exp_f32_e32 v0, v0
	v_exp_f32_e32 v1, v1
	v_pk_mul_f32 v[2:3], v[2:3], v[16:17] op_sel_hi:[1,0]
	v_pk_mul_f32 v[14:15], v[14:15], v[6:7]
	v_exp_f32_e32 v2, v2
	v_exp_f32_e32 v3, v3
	v_pk_mul_f32 v[6:7], v[6:7], v[16:17] op_sel_hi:[1,0]
	v_pk_fma_f32 v[4:5], v[4:5], v[246:247], v[246:247] op_sel_hi:[1,0,0]
	v_exp_f32_e32 v6, v6
	v_exp_f32_e32 v7, v7
	v_pk_fma_f32 v[0:1], v[0:1], v[246:247], v[246:247] op_sel_hi:[1,0,0]
	v_rcp_f32_e32 v4, v4
	v_rcp_f32_e32 v5, v5
	v_rcp_f32_e32 v0, v0
	v_rcp_f32_e32 v1, v1
	v_pk_fma_f32 v[2:3], v[2:3], v[246:247], v[246:247] op_sel_hi:[1,0,0]
	v_rcp_f32_e32 v2, v2
	v_rcp_f32_e32 v3, v3
	v_pk_fma_f32 v[6:7], v[6:7], v[246:247], v[246:247] op_sel_hi:[1,0,0]
	v_rcp_f32_e32 v6, v6
	v_rcp_f32_e32 v7, v7
	v_pk_mul_f32 v[4:5], v[12:13], v[4:5]
	v_pk_mul_f32 v[8:9], v[8:9], v[0:1]
	v_pk_mul_f32 v[10:11], v[10:11], v[2:3]
	v_cvt_pk_bf16_f32 v0, v4, v5
	v_mad_i64_i32 v[4:5], s[46:47], v140, s61, v[112:113]
	v_lshl_add_u64 v[4:5], v[4:5], 0, v[114:115]
	s_and_b64 vcc, exec, s[2:3]
	s_mov_b64 s[2:3], -1
	v_pk_mul_f32 v[6:7], v[14:15], v[6:7]
	s_nop 0
	v_cvt_pk_bf16_f32 v1, v6, v7
	v_cvt_pk_bf16_f32 v2, v8, v9
	v_cvt_pk_bf16_f32 v3, v10, v11
	global_store_dwordx4 v[4:5], v[0:3], off
	s_cbranch_vccnz .LBB0_1289
	s_nop 0
	v_or_b32_e32 v0, v157, v155
	v_or_b32_e32 v1, v156, v154
	v_or3_b32 v0, v0, v151, v153
	v_or3_b32 v1, v1, v150, v152
	v_or3_b32 v0, v0, v147, v149
	v_or3_b32 v1, v1, v146, v148
	s_andn2_b64 vcc, exec, s[4:5]
	v_or3_b32 v0, v0, v143, v145
	v_or3_b32 v1, v1, v142, v144
	s_cbranch_vccnz .LBB0_1288
	s_barrier
	s_branch .LBB0_1288
